# attention item table re-dealt from a cost model with SIMD-pair tile maxima and per-tile / per-item overheads (4 items per workgroup)
# baseline (speedup 1.0000x reference)
.Ltbl:
	s_and_b32 s0, s73, 15
	s_mov_b32 s100, 0x405579f2
	s_cmp_eq_u32 s0, 1
	s_cselect_b32 s100, 0x4010abbb, s100
	s_cmp_eq_u32 s0, 2
	s_cselect_b32 s100, 0x403e0736, s100
	s_cmp_eq_u32 s0, 3
	s_cselect_b32 s100, 0x401d38f7, s100
	s_cmp_eq_u32 s0, 4
	s_cselect_b32 s100, 0x40228aad, s100
	s_cmp_eq_u32 s0, 5
	s_cselect_b32 s100, 0x40512c2b, s100
	s_cmp_eq_u32 s0, 6
	s_cselect_b32 s100, 0x400dfa75, s100
	s_cmp_eq_u32 s0, 7
	s_cselect_b32 s100, 0x4039996c, s100
	s_cmp_eq_u32 s0, 8
	s_cselect_b32 s100, 0x4001be6f, s100
	s_cmp_eq_u32 s0, 9
	s_cselect_b32 s100, 0x4025ac7a, s100
	s_cmp_eq_u32 s0, 10
	s_cselect_b32 s100, 0x401567bc, s100
	s_cmp_eq_u32 s0, 11
	s_cselect_b32 s100, 0x40091e3e, s100
	s_cmp_eq_u32 s0, 12
	s_cselect_b32 s100, 0x4005d8b3, s100
	s_cmp_eq_u32 s0, 13
	s_cselect_b32 s100, 0x403509b4, s100
	s_cmp_eq_u32 s0, 14
	s_cselect_b32 s100, 0x4018b93d, s100
	s_cmp_eq_u32 s0, 15
	s_cselect_b32 s100, 0x4031887f, s100
	s_mov_b32 s74, 0
